# row loops (mode 1): wave_sum butterfly via DPP quad_perm/row_mirror + v_permlane16/32_swap instead of six ds_bpermute round trips (on top of v40)
# baseline (speedup 1.0000x reference)
; __device__ __forceinline__ float h_lo(unsigned w) { return (float)__builtin_bit_cast(h16x2, w).x; }
; __device__ __forceinline__ float h_hi(unsigned w) { return (float)__builtin_bit_cast(h16x2, w).y; }
; __device__ __forceinline__ void rows_one(CP pp, int mode, int r, int has_pre, const f32x4 (&gg)[4], const f32x4 (&pa)[4], const f32x4 (&pb)[4], int lane) {
;     ...
;         const u32x2* yr = (const u32x2*)((const bf16_t*)(pp->ws + WS_Y) + (size_t)r * D) + lane;
;         f32x4 y[4]; float ss = 0.f;
; #pragma unroll
;         for (int j = 0; j < 4; ++j) { const u32x2 w = __builtin_nontemporal_load(yr + 64 * j); const u32x2 xw_ = __builtin_nontemporal_load(xrow + 64 * j); v[j] = (f32x4){h_lo(xw_.x), h_hi(xw_.x), h_lo(xw_.y), h_hi(xw_.y)}; y[j] = (f32x4){bf_lo(w.x), bf_hi(w.x), bf_lo(w.y), bf_hi(w.y)}; ss += (y[j][0] * y[j][0] + y[j][1] * y[j][1]) + (y[j][2] * y[j][2] + y[j][3] * y[j][3]); }
;         const float rstd = 1.0f / sqrtf(wave_sum(ss) * (1.0f / D) + EPS);
; #pragma unroll
;         for (int j = 0; j < 4; ++j) v[j] = v[j] + gg[j] * (y[j] * rstd);
;     }
;     if (has_pre) {
; #pragma unroll
;         for (int j = 0; j < 4; ++j) { u32x2 w; w.x = pk2h(v[j][0], v[j][1]); w.y = pk2h(v[j][2], v[j][3]); __builtin_nontemporal_store(w, xrow + 64 * j); }
.LBB0_351:
	v_add_u32_e32 v70, v87, v86
	v_ashrrev_i32_e32 v71, 31, v70
	v_lshlrev_b64 v[16:17], 11, v[70:71]
	v_lshl_add_u64 v[18:19], v[66:67], 0, v[16:17]
	global_load_dwordx2 v[20:21], v[18:19], off nt
	global_load_dwordx2 v[22:23], v[18:19], off offset:512 nt
	global_load_dwordx2 v[24:25], v[18:19], off offset:1024 nt
	global_load_dwordx2 v[26:27], v[18:19], off offset:1536 nt
	v_lshl_add_u64 v[72:73], v[64:65], 0, v[16:17]
	global_load_dwordx2 v[80:81], v[72:73], off nt
	global_load_dwordx2 v[76:77], v[72:73], off offset:512 nt
	global_load_dwordx2 v[30:31], v[72:73], off offset:1024 nt
	global_load_dwordx2 v[78:79], v[72:73], off offset:1536 nt
	s_waitcnt vmcnt(7)
	v_and_b32_e32 v17, 0xffff0000, v20
	v_and_b32_e32 v19, 0xffff0000, v21
	v_lshlrev_b32_e32 v16, 16, v20
	v_lshlrev_b32_e32 v18, 16, v21
	s_waitcnt vmcnt(6)
	v_lshlrev_b32_e32 v75, 16, v23
	v_and_b32_e32 v21, 0xffff0000, v23
	v_and_b32_e32 v20, 0xffff0000, v22
	s_waitcnt vmcnt(5)
	v_and_b32_e32 v23, 0xffff0000, v24
	s_waitcnt vmcnt(4)
	v_lshlrev_b32_e32 v83, 16, v26
	v_and_b32_e32 v29, 0xffff0000, v26
	v_mul_f32_e32 v28, v19, v19
	v_mul_f32_e32 v82, v17, v17
	v_lshlrev_b32_e32 v74, 16, v22
	v_lshlrev_b32_e32 v22, 16, v24
	v_lshlrev_b32_e32 v24, 16, v25
	v_and_b32_e32 v25, 0xffff0000, v25
	v_pk_mul_f32 v[94:95], v[20:21], v[20:21]
	v_mov_b32_e32 v97, v83
	v_mul_f32_e32 v96, v23, v23
	v_pk_fma_f32 v[100:101], v[18:19], v[18:19], v[28:29] op_sel_hi:[1,1,0]
	v_pk_fma_f32 v[102:103], v[16:17], v[16:17], v[82:83] op_sel_hi:[1,1,0]
	v_lshlrev_b32_e32 v26, 16, v27
	v_and_b32_e32 v27, 0xffff0000, v27
	v_mul_f32_e32 v98, v25, v25
	v_pk_fma_f32 v[94:95], v[74:75], v[74:75], v[94:95]
	v_pk_fma_f32 v[104:105], v[22:23], v[22:23], v[96:97] op_sel_hi:[1,1,0]
	v_mov_b32_e32 v82, v102
	v_mov_b32_e32 v96, v100
	v_mul_f32_e32 v106, v29, v29
	v_mul_f32_e32 v107, v26, v26
	v_mul_f32_e32 v108, v27, v27
	v_pk_fma_f32 v[98:99], v[24:25], v[24:25], v[98:99] op_sel_hi:[1,1,0]
	v_pk_add_f32 v[100:101], v[102:103], v[100:101]
	v_pk_add_f32 v[94:95], v[94:95], v[94:95] op_sel:[0,1] op_sel_hi:[1,0]
	v_pk_mul_f32 v[96:97], v[82:83], v[96:97]
	v_mov_b32_e32 v105, v107
	v_mov_b32_e32 v99, v108
	v_mov_b32_e32 v95, v106
	v_mov_b32_e32 v101, v97
	v_pk_add_f32 v[98:99], v[104:105], v[98:99]
	v_pk_add_f32 v[94:95], v[100:101], v[94:95]
	s_waitcnt vmcnt(1)
	v_cvt_f32_f16_e32 v100, v31
	v_pk_add_f32 v[94:95], v[94:95], v[98:99]
	v_cvt_f32_f16_e32 v98, v30
	v_add_f32_e32 v28, v94, v95
	s_nop 1
	v_mov_b32_dpp v82, v28 quad_perm:[1,0,3,2] row_mask:0xf bank_mask:0xf
	v_cvt_f32_f16_sdwa v99, v30 dst_sel:DWORD dst_unused:UNUSED_PAD src0_sel:WORD_1
	v_cvt_f32_f16_sdwa v101, v31 dst_sel:DWORD dst_unused:UNUSED_PAD src0_sel:WORD_1
	v_mov_b32_e32 v31, v20
	v_mov_b32_e32 v20, v75
	s_waitcnt lgkmcnt(0)
	v_add_f32_e32 v28, v28, v82
	s_nop 1
	v_mov_b32_dpp v82, v28 quad_perm:[2,3,0,1] row_mask:0xf bank_mask:0xf
	v_cndmask_b32_e64 v94, 0, 1, s[68:69]
	v_cmp_ne_u32_e64 s[8:9], 1, v94
	v_cvt_f32_f16_e32 v94, v80
	v_cvt_f32_f16_sdwa v95, v80 dst_sel:DWORD dst_unused:UNUSED_PAD src0_sel:WORD_1
	s_waitcnt lgkmcnt(0)
	v_add_f32_e32 v28, v28, v82
	s_nop 1
	v_mov_b32_dpp v82, v28 row_half_mirror row_mask:0xf bank_mask:0xf
	v_cvt_f32_f16_e32 v80, v81
	v_cvt_f32_f16_sdwa v81, v81 dst_sel:DWORD dst_unused:UNUSED_PAD src0_sel:WORD_1
	v_cvt_f32_f16_e32 v96, v76
	v_cvt_f32_f16_sdwa v97, v76 dst_sel:DWORD dst_unused:UNUSED_PAD src0_sel:WORD_1
	s_waitcnt lgkmcnt(0)
	v_add_f32_e32 v28, v28, v82
	s_nop 1
	v_mov_b32_dpp v82, v28 row_mirror row_mask:0xf bank_mask:0xf
	v_cvt_f32_f16_e32 v76, v77
	v_cvt_f32_f16_sdwa v77, v77 dst_sel:DWORD dst_unused:UNUSED_PAD src0_sel:WORD_1
	s_waitcnt vmcnt(0)
	v_cvt_f32_f16_e32 v102, v78
	v_cvt_f32_f16_sdwa v103, v78 dst_sel:DWORD dst_unused:UNUSED_PAD src0_sel:WORD_1
	s_waitcnt lgkmcnt(0)
	v_add_f32_e32 v28, v28, v82
	v_mov_b32_e32 v82, v28
	s_nop 1
	v_permlane16_swap_b32_e32 v82, v28
	v_cvt_f32_f16_e32 v78, v79
	v_cvt_f32_f16_sdwa v79, v79 dst_sel:DWORD dst_unused:UNUSED_PAD src0_sel:WORD_1
	s_waitcnt lgkmcnt(0)
	v_add_f32_e32 v28, v28, v82
	v_mov_b32_e32 v30, v28
	s_nop 1
	v_permlane32_swap_b32_e32 v30, v28
	s_waitcnt lgkmcnt(0)
	v_add_f32_e32 v28, v28, v30
	v_fmamk_f32 v28, v28, 0x3a800000, v165
	v_mul_f32_e32 v30, 0x4f800000, v28
	v_cmp_gt_f32_e32 vcc, s44, v28
	s_nop 1
	v_cndmask_b32_e32 v28, v28, v30, vcc
	v_sqrt_f32_e32 v82, v28
	v_mov_b32_e32 v30, v74
	v_add_u32_e32 v74, -1, v82
	v_add_u32_e32 v75, 1, v82
	v_fma_f32 v104, -v74, v82, v28
	v_fma_f32 v105, -v75, v82, v28
	v_cmp_ge_f32_e64 s[10:11], 0, v104
	s_nop 1
	v_cndmask_b32_e64 v74, v82, v74, s[10:11]
	v_cmp_lt_f32_e64 s[10:11], 0, v105
	s_nop 1
	v_cndmask_b32_e64 v74, v74, v75, s[10:11]
	v_mul_f32_e32 v75, 0x37800000, v74
	v_cndmask_b32_e32 v74, v74, v75, vcc
	v_cmp_class_f32_e32 vcc, v28, v167
	s_nop 1
	v_cndmask_b32_e32 v74, v74, v28, vcc
	v_div_scale_f32 v75, s[10:11], v74, v74, 1.0
	v_rcp_f32_e32 v82, v75
	v_mov_b32_e32 v28, v83
	v_div_scale_f32 v83, vcc, 1.0, v74, 1.0
	v_fma_f32 v104, -v75, v82, 1.0
	v_fmac_f32_e32 v82, v104, v82
	v_mul_f32_e32 v104, v83, v82
	v_fma_f32 v105, -v75, v104, v83
	v_fmac_f32_e32 v104, v105, v82
	v_fma_f32 v75, -v75, v104, v83
	v_div_fmas_f32 v75, v75, v82, v104
	v_div_fixup_f32 v74, v75, v74, 1.0
	v_pk_mul_f32 v[16:17], v[74:75], v[16:17] op_sel_hi:[0,1]
	v_pk_mul_f32 v[18:19], v[74:75], v[18:19] op_sel_hi:[0,1]
	v_pk_mul_f32 v[82:83], v[74:75], v[30:31] op_sel_hi:[0,1]
	v_pk_mul_f32 v[20:21], v[74:75], v[20:21] op_sel_hi:[0,1]
	v_pk_mul_f32 v[104:105], v[74:75], v[22:23] op_sel_hi:[0,1]
	v_pk_mul_f32 v[22:23], v[74:75], v[24:25] op_sel_hi:[0,1]
	v_pk_mul_f32 v[106:107], v[28:29], v[74:75] op_sel_hi:[1,0]
	v_pk_mul_f32 v[74:75], v[26:27], v[74:75] op_sel_hi:[1,0]
	s_andn2_b64 vcc, exec, s[68:69]
	v_pk_fma_f32 v[30:31], v[40:41], v[18:19], v[80:81]
	v_pk_fma_f32 v[28:29], v[42:43], v[16:17], v[94:95]
	v_pk_fma_f32 v[26:27], v[32:33], v[20:21], v[76:77]
	v_pk_fma_f32 v[24:25], v[34:35], v[82:83], v[96:97]
	v_pk_fma_f32 v[22:23], v[36:37], v[22:23], v[100:101]
	v_pk_fma_f32 v[20:21], v[38:39], v[104:105], v[98:99]
	v_pk_fma_f32 v[18:19], v[44:45], v[74:75], v[78:79]
	v_pk_fma_f32 v[16:17], v[46:47], v[106:107], v[102:103]
	s_mov_b64 s[10:11], -1
	s_cbranch_vccnz .LBB0_354
	v_cvt_pk_f16_f32 v74, v28, v29
	v_cvt_pk_f16_f32 v75, v30, v31
	global_store_dwordx2 v[72:73], v[74:75], off nt
	v_cvt_pk_f16_f32 v74, v24, v25
	v_cvt_pk_f16_f32 v75, v26, v27
	global_store_dwordx2 v[72:73], v[74:75], off offset:512 nt
	v_cvt_pk_f16_f32 v74, v20, v21
	v_cvt_pk_f16_f32 v75, v22, v23
	global_store_dwordx2 v[72:73], v[74:75], off offset:1024 nt
	v_cvt_pk_f16_f32 v74, v16, v17
	v_cvt_pk_f16_f32 v75, v18, v19
	global_store_dwordx2 v[72:73], v[74:75], off offset:1536 nt
	v_lshlrev_b64 v[70:71], 10, v[70:71]
	s_cbranch_execz .LBB0_355

; __device__ __forceinline__ unsigned pk2(float lo, float hi) { return pg8::cvt_pk_bf16(lo, hi); }
; __device__ __forceinline__ void rows_one(CP pp, int mode, int r, int has_pre, const f32x4 (&gg)[4], const f32x4 (&pa)[4], const f32x4 (&pb)[4], int lane) {
;     ...
;     if (has_pre) {
;         float ss = 0.f;
; #pragma unroll
;         for (int j = 0; j < 4; ++j) ss += (v[j][0] * v[j][0] + v[j][1] * v[j][1]) + (v[j][2] * v[j][2] + v[j][3] * v[j][3]);
;         const float rstd = 1.0f / sqrtf(wave_sum(ss) * (1.0f / D) + EPS);
;         u32x2* ho = (u32x2*)((bf16_t*)(pp->ws + WS_H) + (size_t)r * D) + lane;
; #pragma unroll
;         for (int j = 0; j < 4; ++j) { const f32x4 h = (v[j] * rstd) * pa[j] + pb[j]; u32x2 w; w.x = pk2(h[0], h[1]); w.y = pk2(h[2], h[3]); __builtin_nontemporal_store(w, ho + 64 * j); }
;     }
.LBB0_356:
	v_pk_mul_f32 v[72:73], v[30:31], v[30:31]
	v_pk_mul_f32 v[74:75], v[28:29], v[28:29]
	v_lshl_add_u64 v[70:71], v[70:71], 1, v[68:69]
	v_pk_mov_b32 v[76:77], v[74:75], v[72:73] op_sel:[1,0]
	v_mov_b32_e32 v75, v73
	v_pk_add_f32 v[72:73], v[76:77], v[74:75]
	v_pk_mul_f32 v[74:75], v[26:27], v[26:27]
	v_pk_add_f32 v[72:73], v[72:73], v[72:73] op_sel_hi:[0,1]
	v_pk_mul_f32 v[76:77], v[24:25], v[24:25]
	v_mul_f32_e32 v72, v20, v20
	v_pk_mov_b32 v[78:79], v[76:77], v[74:75] op_sel:[1,0]
	v_mov_b32_e32 v77, v75
	v_pk_add_f32 v[74:75], v[78:79], v[76:77]
	v_pk_fma_f32 v[76:77], v[20:21], v[20:21], v[72:73] op_sel_hi:[1,1,0]
	v_mul_f32_e32 v72, v22, v22
	v_pk_add_f32 v[74:75], v[74:75], v[74:75] op_sel_hi:[0,1]
	v_pk_fma_f32 v[78:79], v[22:23], v[22:23], v[72:73] op_sel_hi:[1,1,0]
	v_mul_f32_e32 v76, v16, v16
	v_mul_f32_e32 v78, v17, v17
	v_mul_f32_e32 v72, v18, v18
	v_mul_f32_e32 v74, v19, v19
	v_pk_add_f32 v[76:77], v[76:77], v[78:79]
	v_pk_add_f32 v[72:73], v[72:73], v[74:75]
	s_nop 0
	v_pk_add_f32 v[72:73], v[76:77], v[72:73]
	s_nop 0
	v_add_f32_e32 v72, v72, v73
	s_nop 1
	v_mov_b32_dpp v73, v72 quad_perm:[1,0,3,2] row_mask:0xf bank_mask:0xf
	s_waitcnt lgkmcnt(0)
	v_add_f32_e32 v72, v72, v73
	s_nop 1
	v_mov_b32_dpp v73, v72 quad_perm:[2,3,0,1] row_mask:0xf bank_mask:0xf
	s_waitcnt lgkmcnt(0)
	v_add_f32_e32 v72, v72, v73
	s_nop 1
	v_mov_b32_dpp v73, v72 row_half_mirror row_mask:0xf bank_mask:0xf
	s_waitcnt lgkmcnt(0)
	v_add_f32_e32 v72, v72, v73
	s_nop 1
	v_mov_b32_dpp v73, v72 row_mirror row_mask:0xf bank_mask:0xf
	s_waitcnt lgkmcnt(0)
	v_add_f32_e32 v72, v72, v73
	v_mov_b32_e32 v73, v72
	s_nop 1
	v_permlane16_swap_b32_e32 v73, v72
	s_waitcnt lgkmcnt(0)
	v_add_f32_e32 v72, v72, v73
	v_mov_b32_e32 v73, v72
	s_nop 1
	v_permlane32_swap_b32_e32 v73, v72
	s_waitcnt lgkmcnt(0)
	v_add_f32_e32 v72, v72, v73
	v_fmamk_f32 v72, v72, 0x3a800000, v165
	v_mul_f32_e32 v73, 0x4f800000, v72
	v_cmp_gt_f32_e32 vcc, s44, v72
	s_nop 1
	v_cndmask_b32_e32 v72, v72, v73, vcc
	v_sqrt_f32_e32 v73, v72
	s_nop 0
	v_add_u32_e32 v74, -1, v73
	v_add_u32_e32 v75, 1, v73
	v_fma_f32 v76, -v74, v73, v72
	v_fma_f32 v77, -v75, v73, v72
	v_cmp_ge_f32_e64 s[8:9], 0, v76
	s_nop 1
	v_cndmask_b32_e64 v73, v73, v74, s[8:9]
	v_cmp_lt_f32_e64 s[8:9], 0, v77
	s_nop 1
	v_cndmask_b32_e64 v73, v73, v75, s[8:9]
	v_mul_f32_e32 v74, 0x37800000, v73
	v_cndmask_b32_e32 v73, v73, v74, vcc
	v_cmp_class_f32_e32 vcc, v72, v167
	s_nop 1
	v_cndmask_b32_e32 v72, v73, v72, vcc
	v_div_scale_f32 v73, s[8:9], v72, v72, 1.0
	v_rcp_f32_e32 v74, v73
	v_div_scale_f32 v75, vcc, 1.0, v72, 1.0
	v_fma_f32 v76, -v73, v74, 1.0
	v_fmac_f32_e32 v74, v76, v74
	v_mul_f32_e32 v76, v75, v74
	v_fma_f32 v77, -v73, v76, v75
	v_fmac_f32_e32 v76, v77, v74
	v_fma_f32 v73, -v73, v76, v75
	v_div_fmas_f32 v73, v73, v74, v76
	v_div_fixup_f32 v72, v73, v72, 1.0
	v_pk_mul_f32 v[28:29], v[28:29], v[72:73] op_sel_hi:[1,0]
	v_pk_mul_f32 v[24:25], v[24:25], v[72:73] op_sel_hi:[1,0]
	v_pk_mul_f32 v[20:21], v[20:21], v[72:73] op_sel_hi:[1,0]
	v_pk_mul_f32 v[16:17], v[16:17], v[72:73] op_sel_hi:[1,0]
	v_pk_mul_f32 v[30:31], v[30:31], v[72:73] op_sel_hi:[1,0]
	v_pk_fma_f32 v[28:29], v[48:49], v[28:29], v[0:1]
	v_pk_mul_f32 v[26:27], v[26:27], v[72:73] op_sel_hi:[1,0]
	v_pk_fma_f32 v[24:25], v[52:53], v[24:25], v[4:5]
	v_pk_mul_f32 v[22:23], v[22:23], v[72:73] op_sel_hi:[1,0]
	v_pk_fma_f32 v[20:21], v[56:57], v[20:21], v[8:9]
	v_pk_mul_f32 v[18:19], v[18:19], v[72:73] op_sel_hi:[1,0]
	v_pk_fma_f32 v[16:17], v[60:61], v[16:17], v[12:13]
	v_pk_fma_f32 v[30:31], v[50:51], v[30:31], v[2:3]
	v_cvt_pk_bf16_f32 v28, v28, v29
	v_pk_fma_f32 v[26:27], v[54:55], v[26:27], v[6:7]
	v_cvt_pk_bf16_f32 v29, v30, v31
	global_store_dwordx2 v[70:71], v[28:29], off nt
	v_cvt_pk_bf16_f32 v24, v24, v25
	v_cvt_pk_bf16_f32 v25, v26, v27
	global_store_dwordx2 v[70:71], v[24:25], off offset:512 nt
	v_pk_fma_f32 v[22:23], v[58:59], v[22:23], v[10:11]
	v_cvt_pk_bf16_f32 v20, v20, v21
	v_pk_fma_f32 v[18:19], v[62:63], v[18:19], v[14:15]
	v_cvt_pk_bf16_f32 v21, v22, v23
	global_store_dwordx2 v[70:71], v[20:21], off offset:1024 nt
	v_cvt_pk_bf16_f32 v16, v16, v17
	v_cvt_pk_bf16_f32 v17, v18, v19
	global_store_dwordx2 v[70:71], v[16:17], off offset:1536 nt
	s_branch .LBB0_350

; __device__ __forceinline__ float h_lo(unsigned w) { return (float)__builtin_bit_cast(h16x2, w).x; }
; __device__ __forceinline__ float h_hi(unsigned w) { return (float)__builtin_bit_cast(h16x2, w).y; }
; __device__ __forceinline__ void rows_one(CP pp, int mode, int r, int has_pre, const f32x4 (&gg)[4], const f32x4 (&pa)[4], const f32x4 (&pb)[4], int lane) {
;     ...
;         const u32x2* yr = (const u32x2*)((const bf16_t*)(pp->ws + WS_Y) + (size_t)r * D) + lane;
;         f32x4 y[4]; float ss = 0.f;
; #pragma unroll
;         for (int j = 0; j < 4; ++j) { const u32x2 w = __builtin_nontemporal_load(yr + 64 * j); const u32x2 xw_ = __builtin_nontemporal_load(xrow + 64 * j); v[j] = (f32x4){h_lo(xw_.x), h_hi(xw_.x), h_lo(xw_.y), h_hi(xw_.y)}; y[j] = (f32x4){bf_lo(w.x), bf_hi(w.x), bf_lo(w.y), bf_hi(w.y)}; ss += (y[j][0] * y[j][0] + y[j][1] * y[j][1]) + (y[j][2] * y[j][2] + y[j][3] * y[j][3]); }
;         const float rstd = 1.0f / sqrtf(wave_sum(ss) * (1.0f / D) + EPS);
; #pragma unroll
;         for (int j = 0; j < 4; ++j) v[j] = v[j] + gg[j] * (y[j] * rstd);
;     }
;     if (has_pre) {
; #pragma unroll
;         for (int j = 0; j < 4; ++j) { u32x2 w; w.x = pk2h(v[j][0], v[j][1]); w.y = pk2h(v[j][2], v[j][3]); __builtin_nontemporal_store(w, xrow + 64 * j); }
; __device__ __forceinline__ void phase_rows(CP pp, int mode, int rows, int li, int k, float wgt, int has_pre, int li2, int k2) {
;     ...
;         for (int rc = gw; rc < NCTX; rc += NGW) rows_one(pp, mode, NLAT + rc, has_pre, gg, pa, pb, lane);
.LBB0_363:
	global_load_dwordx2 v[18:19], v[66:67], off nt
	global_load_dwordx2 v[20:21], v[66:67], off offset:512 nt
	global_load_dwordx2 v[24:25], v[66:67], off offset:1024 nt
	global_load_dwordx2 v[26:27], v[66:67], off offset:1536 nt
	v_add_co_u32_e32 v16, vcc, 0x8400000, v66
	s_waitcnt vmcnt(2)
	v_lshlrev_b32_e32 v79, 16, v21
	v_addc_co_u32_e32 v17, vcc, 0, v67, vcc
	global_load_dwordx2 v[28:29], v[16:17], off nt
	global_load_dwordx2 v[30:31], v[16:17], off offset:512 nt
	global_load_dwordx2 v[74:75], v[16:17], off offset:1024 nt
	global_load_dwordx2 v[76:77], v[16:17], off offset:1536 nt
	v_lshlrev_b32_e32 v16, 16, v18
	v_and_b32_e32 v17, 0xffff0000, v18
	v_lshlrev_b32_e32 v18, 16, v19
	v_and_b32_e32 v19, 0xffff0000, v19
	v_lshlrev_b32_e32 v78, 16, v20
	v_and_b32_e32 v21, 0xffff0000, v21
	v_and_b32_e32 v20, 0xffff0000, v20
	s_waitcnt vmcnt(5)
	v_and_b32_e32 v23, 0xffff0000, v24
	s_waitcnt vmcnt(4)
	v_lshlrev_b32_e32 v81, 16, v26
	v_and_b32_e32 v83, 0xffff0000, v26
	v_mul_f32_e32 v80, v19, v19
	v_mul_f32_e32 v82, v17, v17
	v_lshlrev_b32_e32 v22, 16, v24
	v_lshlrev_b32_e32 v24, 16, v25
	v_and_b32_e32 v25, 0xffff0000, v25
	v_pk_mul_f32 v[86:87], v[20:21], v[20:21]
	v_mov_b32_e32 v89, v81
	v_mul_f32_e32 v88, v23, v23
	v_pk_fma_f32 v[92:93], v[18:19], v[18:19], v[80:81] op_sel_hi:[1,1,0]
	v_pk_fma_f32 v[94:95], v[16:17], v[16:17], v[82:83] op_sel_hi:[1,1,0]
	v_lshlrev_b32_e32 v26, 16, v27
	v_and_b32_e32 v27, 0xffff0000, v27
	v_mul_f32_e32 v90, v25, v25
	v_pk_fma_f32 v[86:87], v[78:79], v[78:79], v[86:87]
	v_pk_fma_f32 v[96:97], v[22:23], v[22:23], v[88:89] op_sel_hi:[1,1,0]
	v_mov_b32_e32 v80, v94
	v_mov_b32_e32 v88, v92
	v_mul_f32_e32 v85, v83, v83
	v_mul_f32_e32 v98, v26, v26
	v_mul_f32_e32 v99, v27, v27
	v_pk_fma_f32 v[90:91], v[24:25], v[24:25], v[90:91] op_sel_hi:[1,1,0]
	v_pk_add_f32 v[92:93], v[94:95], v[92:93]
	v_pk_add_f32 v[86:87], v[86:87], v[86:87] op_sel:[0,1] op_sel_hi:[1,0]
	v_pk_mul_f32 v[88:89], v[80:81], v[88:89]
	v_mov_b32_e32 v97, v98
	v_mov_b32_e32 v91, v99
	v_mov_b32_e32 v87, v85
	v_mov_b32_e32 v93, v89
	v_pk_add_f32 v[90:91], v[96:97], v[90:91]
	v_pk_add_f32 v[86:87], v[92:93], v[86:87]
	s_waitcnt vmcnt(2)
	v_cvt_f32_f16_e32 v88, v31
	v_pk_add_f32 v[86:87], v[86:87], v[90:91]
	v_cvt_f32_f16_sdwa v89, v31 dst_sel:DWORD dst_unused:UNUSED_PAD src0_sel:WORD_1
	v_add_f32_e32 v80, v86, v87
	s_nop 1
	v_mov_b32_dpp v82, v80 quad_perm:[1,0,3,2] row_mask:0xf bank_mask:0xf
	v_mov_b32_e32 v86, v78
	v_mov_b32_e32 v87, v20
	v_mov_b32_e32 v20, v79
	v_cvt_f32_f16_e32 v78, v28
	s_waitcnt lgkmcnt(0)
	v_add_f32_e32 v80, v80, v82
	s_nop 1
	v_mov_b32_dpp v82, v80 quad_perm:[2,3,0,1] row_mask:0xf bank_mask:0xf
	v_cvt_f32_f16_sdwa v79, v28 dst_sel:DWORD dst_unused:UNUSED_PAD src0_sel:WORD_1
	v_cvt_f32_f16_e32 v28, v29
	v_cvt_f32_f16_sdwa v29, v29 dst_sel:DWORD dst_unused:UNUSED_PAD src0_sel:WORD_1
	s_waitcnt vmcnt(1)
	v_cvt_f32_f16_sdwa v91, v74 dst_sel:DWORD dst_unused:UNUSED_PAD src0_sel:WORD_1
	s_waitcnt lgkmcnt(0)
	v_add_f32_e32 v80, v80, v82
	s_nop 1
	v_mov_b32_dpp v85, v80 row_half_mirror row_mask:0xf bank_mask:0xf
	v_mov_b32_e32 v82, v81
	s_waitcnt vmcnt(0)
	v_cvt_f32_f16_e32 v92, v76
	v_cvt_f32_f16_sdwa v93, v76 dst_sel:DWORD dst_unused:UNUSED_PAD src0_sel:WORD_1
	v_cvt_f32_f16_e32 v76, v77
	s_waitcnt lgkmcnt(0)
	v_add_f32_e32 v80, v80, v85
	s_nop 1
	v_mov_b32_dpp v81, v80 row_mirror row_mask:0xf bank_mask:0xf
	v_cvt_f32_f16_sdwa v77, v77 dst_sel:DWORD dst_unused:UNUSED_PAD src0_sel:WORD_1
	s_waitcnt lgkmcnt(0)
	v_add_f32_e32 v85, v80, v81
	v_mov_b32_e32 v90, v85
	s_nop 1
	v_permlane16_swap_b32_e32 v90, v85
	v_cvt_f32_f16_e32 v80, v30
	v_cvt_f32_f16_sdwa v81, v30 dst_sel:DWORD dst_unused:UNUSED_PAD src0_sel:WORD_1
	s_waitcnt lgkmcnt(0)
	v_add_f32_e32 v30, v85, v90
	v_mov_b32_e32 v31, v30
	s_nop 1
	v_permlane32_swap_b32_e32 v31, v30
	v_cvt_f32_f16_e32 v90, v74
	v_cvt_f32_f16_e32 v74, v75
	v_cvt_f32_f16_sdwa v75, v75 dst_sel:DWORD dst_unused:UNUSED_PAD src0_sel:WORD_1
	s_waitcnt lgkmcnt(0)
	v_add_f32_e32 v30, v30, v31
	v_fmamk_f32 v30, v30, 0x3a800000, v165
	v_mul_f32_e32 v31, 0x4f800000, v30
	v_cmp_gt_f32_e32 vcc, s44, v30
	s_nop 1
	v_cndmask_b32_e32 v30, v30, v31, vcc
	v_sqrt_f32_e32 v31, v30
	s_nop 0
	v_add_u32_e32 v85, -1, v31
	v_add_u32_e32 v94, 1, v31
	v_fma_f32 v95, -v85, v31, v30
	v_fma_f32 v96, -v94, v31, v30
	v_cmp_ge_f32_e64 s[10:11], 0, v95
	s_nop 1
	v_cndmask_b32_e64 v31, v31, v85, s[10:11]
	v_cmp_lt_f32_e64 s[10:11], 0, v96
	s_nop 1
	v_cndmask_b32_e64 v31, v31, v94, s[10:11]
	v_mul_f32_e32 v85, 0x37800000, v31
	v_cndmask_b32_e32 v31, v31, v85, vcc
	v_cmp_class_f32_e32 vcc, v30, v167
	s_mov_b64 s[10:11], -1
	s_nop 0
	v_cndmask_b32_e32 v30, v31, v30, vcc
	v_div_scale_f32 v31, s[4:5], v30, v30, 1.0
	v_rcp_f32_e32 v85, v31
	v_div_scale_f32 v94, vcc, 1.0, v30, 1.0
	v_fma_f32 v95, -v31, v85, 1.0
	v_fmac_f32_e32 v85, v95, v85
	v_mul_f32_e32 v95, v94, v85
	v_fma_f32 v96, -v31, v95, v94
	v_fmac_f32_e32 v95, v96, v85
	v_fma_f32 v31, -v31, v95, v94
	v_div_fmas_f32 v31, v31, v85, v95
	v_div_fixup_f32 v30, v31, v30, 1.0
	v_pk_mul_f32 v[16:17], v[30:31], v[16:17] op_sel_hi:[0,1]
	v_pk_mul_f32 v[18:19], v[30:31], v[18:19] op_sel_hi:[0,1]
	v_pk_mul_f32 v[86:87], v[30:31], v[86:87] op_sel_hi:[0,1]
	v_pk_mul_f32 v[20:21], v[30:31], v[20:21] op_sel_hi:[0,1]
	v_pk_mul_f32 v[94:95], v[30:31], v[22:23] op_sel_hi:[0,1]
	v_pk_mul_f32 v[22:23], v[30:31], v[24:25] op_sel_hi:[0,1]
	v_pk_mul_f32 v[82:83], v[82:83], v[30:31] op_sel_hi:[1,0]
	v_pk_mul_f32 v[96:97], v[26:27], v[30:31] op_sel_hi:[1,0]
	s_and_b64 vcc, exec, s[8:9]
	v_pk_fma_f32 v[30:31], v[40:41], v[18:19], v[28:29]
	v_pk_fma_f32 v[28:29], v[42:43], v[16:17], v[78:79]
	v_pk_fma_f32 v[26:27], v[32:33], v[20:21], v[88:89]
	v_pk_fma_f32 v[24:25], v[34:35], v[86:87], v[80:81]
	v_pk_fma_f32 v[22:23], v[36:37], v[22:23], v[74:75]
	v_pk_fma_f32 v[20:21], v[38:39], v[94:95], v[90:91]
	v_pk_fma_f32 v[18:19], v[44:45], v[96:97], v[76:77]
	v_pk_fma_f32 v[16:17], v[46:47], v[82:83], v[92:93]
	s_cbranch_vccnz .LBB0_366
	s_mov_b64 s[4:5], 0x8400000
	v_lshl_add_u64 v[74:75], v[66:67], 0, s[4:5]
	s_mov_b64 s[4:5], 0x8400200
	v_cvt_pk_f16_f32 v82, v28, v29
	v_cvt_pk_f16_f32 v83, v30, v31
	v_lshl_add_u64 v[76:77], v[66:67], 0, s[4:5]
	s_mov_b64 s[4:5], 0x8400400
	global_store_dwordx2 v[74:75], v[82:83], off nt
	v_cvt_pk_f16_f32 v74, v24, v25
	v_cvt_pk_f16_f32 v75, v26, v27
	v_lshl_add_u64 v[78:79], v[66:67], 0, s[4:5]
	s_mov_b64 s[4:5], 0x8400600
	global_store_dwordx2 v[76:77], v[74:75], off nt
	v_cvt_pk_f16_f32 v74, v20, v21
	v_cvt_pk_f16_f32 v75, v22, v23
	v_lshl_add_u64 v[80:81], v[66:67], 0, s[4:5]
	global_store_dwordx2 v[78:79], v[74:75], off nt
	v_cvt_pk_f16_f32 v74, v16, v17
	v_cvt_pk_f16_f32 v75, v18, v19
	global_store_dwordx2 v[80:81], v[74:75], off nt
	s_cbranch_execz .LBB0_367

; __device__ __forceinline__ unsigned pk2(float lo, float hi) { return pg8::cvt_pk_bf16(lo, hi); }
; __device__ __forceinline__ void rows_one(CP pp, int mode, int r, int has_pre, const f32x4 (&gg)[4], const f32x4 (&pa)[4], const f32x4 (&pb)[4], int lane) {
;     ...
;     if (has_pre) {
;         float ss = 0.f;
; #pragma unroll
;         for (int j = 0; j < 4; ++j) ss += (v[j][0] * v[j][0] + v[j][1] * v[j][1]) + (v[j][2] * v[j][2] + v[j][3] * v[j][3]);
;         const float rstd = 1.0f / sqrtf(wave_sum(ss) * (1.0f / D) + EPS);
;         u32x2* ho = (u32x2*)((bf16_t*)(pp->ws + WS_H) + (size_t)r * D) + lane;
; #pragma unroll
;         for (int j = 0; j < 4; ++j) { const f32x4 h = (v[j] * rstd) * pa[j] + pb[j]; u32x2 w; w.x = pk2(h[0], h[1]); w.y = pk2(h[2], h[3]); __builtin_nontemporal_store(w, ho + 64 * j); }
;     }
.LBB0_368:
	v_pk_mul_f32 v[74:75], v[30:31], v[30:31]
	v_pk_mul_f32 v[76:77], v[28:29], v[28:29]
	s_mov_b32 s2, 0xf7c00000
	v_pk_mov_b32 v[78:79], v[76:77], v[74:75] op_sel:[1,0]
	v_mov_b32_e32 v77, v75
	v_pk_add_f32 v[74:75], v[78:79], v[76:77]
	v_pk_mul_f32 v[76:77], v[26:27], v[26:27]
	v_pk_add_f32 v[74:75], v[74:75], v[74:75] op_sel_hi:[0,1]
	v_pk_mul_f32 v[78:79], v[24:25], v[24:25]
	v_mul_f32_e32 v74, v20, v20
	v_pk_mov_b32 v[80:81], v[78:79], v[76:77] op_sel:[1,0]
	v_mov_b32_e32 v79, v77
	v_pk_add_f32 v[76:77], v[80:81], v[78:79]
	v_pk_fma_f32 v[78:79], v[20:21], v[20:21], v[74:75] op_sel_hi:[1,1,0]
	v_mul_f32_e32 v74, v22, v22
	v_pk_add_f32 v[76:77], v[76:77], v[76:77] op_sel_hi:[0,1]
	v_pk_fma_f32 v[80:81], v[22:23], v[22:23], v[74:75] op_sel_hi:[1,1,0]
	v_mul_f32_e32 v78, v16, v16
	v_mul_f32_e32 v80, v17, v17
	v_mul_f32_e32 v74, v18, v18
	v_mul_f32_e32 v76, v19, v19
	v_pk_add_f32 v[78:79], v[78:79], v[80:81]
	v_pk_add_f32 v[74:75], v[74:75], v[76:77]
	s_nop 0
	v_pk_add_f32 v[74:75], v[78:79], v[74:75]
	s_nop 0
	v_add_f32_e32 v74, v74, v75
	s_nop 1
	v_mov_b32_dpp v75, v74 quad_perm:[1,0,3,2] row_mask:0xf bank_mask:0xf
	s_waitcnt lgkmcnt(0)
	v_add_f32_e32 v74, v74, v75
	s_nop 1
	v_mov_b32_dpp v75, v74 quad_perm:[2,3,0,1] row_mask:0xf bank_mask:0xf
	s_waitcnt lgkmcnt(0)
	v_add_f32_e32 v74, v74, v75
	s_nop 1
	v_mov_b32_dpp v75, v74 row_half_mirror row_mask:0xf bank_mask:0xf
	s_waitcnt lgkmcnt(0)
	v_add_f32_e32 v74, v74, v75
	s_nop 1
	v_mov_b32_dpp v75, v74 row_mirror row_mask:0xf bank_mask:0xf
	s_waitcnt lgkmcnt(0)
	v_add_f32_e32 v74, v74, v75
	v_mov_b32_e32 v75, v74
	s_nop 1
	v_permlane16_swap_b32_e32 v75, v74
	s_waitcnt lgkmcnt(0)
	v_add_f32_e32 v74, v74, v75
	v_mov_b32_e32 v75, v74
	s_nop 1
	v_permlane32_swap_b32_e32 v75, v74
	s_waitcnt lgkmcnt(0)
	v_add_f32_e32 v74, v74, v75
	v_fmamk_f32 v74, v74, 0x3a800000, v165
	v_mul_f32_e32 v75, 0x4f800000, v74
	v_cmp_gt_f32_e32 vcc, s44, v74
	s_nop 1
	v_cndmask_b32_e32 v74, v74, v75, vcc
	v_sqrt_f32_e32 v75, v74
	s_nop 0
	v_add_u32_e32 v76, -1, v75
	v_add_u32_e32 v77, 1, v75
	v_fma_f32 v78, -v76, v75, v74
	v_fma_f32 v79, -v77, v75, v74
	v_cmp_ge_f32_e64 s[10:11], 0, v78
	s_nop 1
	v_cndmask_b32_e64 v75, v75, v76, s[10:11]
	v_cmp_lt_f32_e64 s[10:11], 0, v79
	s_nop 1
	v_cndmask_b32_e64 v75, v75, v77, s[10:11]
	v_mul_f32_e32 v76, 0x37800000, v75
	v_cndmask_b32_e32 v75, v75, v76, vcc
	v_cmp_class_f32_e32 vcc, v74, v167
	s_nop 1
	v_cndmask_b32_e32 v74, v75, v74, vcc
	v_div_scale_f32 v75, s[4:5], v74, v74, 1.0
	v_rcp_f32_e32 v76, v75
	v_div_scale_f32 v77, vcc, 1.0, v74, 1.0
	v_fma_f32 v78, -v75, v76, 1.0
	v_fmac_f32_e32 v76, v78, v76
	v_mul_f32_e32 v78, v77, v76
	v_fma_f32 v79, -v75, v78, v77
	v_fmac_f32_e32 v78, v79, v76
	v_fma_f32 v75, -v75, v78, v77
	v_div_fmas_f32 v75, v75, v76, v78
	v_div_fixup_f32 v74, v75, v74, 1.0
	v_pk_mul_f32 v[28:29], v[28:29], v[74:75] op_sel_hi:[1,0]
	v_pk_mul_f32 v[30:31], v[30:31], v[74:75] op_sel_hi:[1,0]
	v_pk_fma_f32 v[28:29], v[48:49], v[28:29], v[8:9]
	v_pk_fma_f32 v[30:31], v[50:51], v[30:31], v[10:11]
	v_cvt_pk_bf16_f32 v28, v28, v29
	v_pk_mul_f32 v[24:25], v[24:25], v[74:75] op_sel_hi:[1,0]
	v_cvt_pk_bf16_f32 v29, v30, v31
	v_add_co_u32_e32 v30, vcc, s2, v66
	v_pk_mul_f32 v[26:27], v[26:27], v[74:75] op_sel_hi:[1,0]
	s_nop 0
	v_addc_co_u32_e32 v31, vcc, -1, v67, vcc
	v_pk_fma_f32 v[26:27], v[58:59], v[26:27], v[6:7]
	v_pk_fma_f32 v[24:25], v[56:57], v[24:25], v[4:5]
	s_mov_b32 s2, 0xf7c01000
	global_store_dwordx2 v[30:31], v[28:29], off nt
	v_cvt_pk_bf16_f32 v24, v24, v25
	v_cvt_pk_bf16_f32 v25, v26, v27
	v_add_co_u32_e32 v26, vcc, s2, v66
	v_pk_mul_f32 v[20:21], v[20:21], v[74:75] op_sel_hi:[1,0]
	v_pk_mul_f32 v[16:17], v[16:17], v[74:75] op_sel_hi:[1,0]
	v_addc_co_u32_e32 v27, vcc, -1, v67, vcc
	v_pk_mul_f32 v[22:23], v[22:23], v[74:75] op_sel_hi:[1,0]
	v_pk_fma_f32 v[20:21], v[60:61], v[20:21], v[0:1]
	v_pk_mul_f32 v[18:19], v[18:19], v[74:75] op_sel_hi:[1,0]
	v_pk_fma_f32 v[16:17], v[52:53], v[16:17], v[12:13]
	global_store_dwordx2 v[26:27], v[24:25], off offset:-3584 nt
	v_pk_fma_f32 v[22:23], v[62:63], v[22:23], v[2:3]
	v_cvt_pk_bf16_f32 v20, v20, v21
	v_pk_fma_f32 v[18:19], v[54:55], v[18:19], v[14:15]
	v_cvt_pk_bf16_f32 v21, v22, v23
	global_store_dwordx2 v[26:27], v[20:21], off offset:-3072 nt
	v_cvt_pk_bf16_f32 v16, v16, v17
	v_cvt_pk_bf16_f32 v17, v18, v19
	global_store_dwordx2 v[26:27], v[16:17], off offset:-2560 nt
	s_branch .LBB0_362
